# strategy 4: static s_setprio 1 for waves 4-7 in the FFN-in K-loop, per-phase flips deleted there (on top of v40)
# baseline (speedup 1.0000x reference)
.LBB0_1288:
	s_add_u32 s8, s12, 0x4c00000
	s_addc_u32 s9, s13, 0
	s_add_u32 s10, s12, 0x20000
	s_addc_u32 s11, s13, 0
	s_add_u32 s46, s12, 0x130000
	s_addc_u32 s47, s13, 0
	s_lshl_b32 s12, s17, 5
	s_and_b32 s54, s12, 0x60
	s_mov_b64 s[12:13], 0x80
	s_add_i32 m0, s34, 0x18000
	v_lshl_add_u64 v[8:9], v[8:9], 0, s[12:13]
	s_lshl_b32 s24, s16, 13
	s_lshl_b32 s17, s54, 7
	s_waitcnt vmcnt(2)
	s_barrier
	global_load_lds_dwordx4 v[8:9], off
	v_lshl_add_u64 v[6:7], v[6:7], 0, s[12:13]
	s_add_i32 m0, s34, 0x1a000
	s_add_i32 s55, s34, 0x8000
	s_add_i32 s56, s34, 0xa000
	global_load_lds_dwordx4 v[6:7], off
	v_lshl_add_u64 v[2:3], v[2:3], 0, s[12:13]
	s_mov_b32 m0, s55
	s_add_u32 s18, s22, 0x40080
	global_load_lds_dwordx4 v[2:3], off
	v_lshl_add_u64 v[2:3], v[4:5], 0, s[12:13]
	s_mov_b32 m0, s56
	s_addc_u32 s19, s23, 0
	global_load_lds_dwordx4 v[2:3], off
	s_add_i32 m0, s34, 0x1c000
	v_lshl_add_u64 v[2:3], s[18:19], 0, v[150:151]
	global_load_lds_dwordx4 v[2:3], off
	v_lshl_add_u64 v[2:3], s[18:19], 0, v[146:147]
	s_add_i32 m0, s34, 0x1e000
	s_cmpk_lt_u32 s15, 0x100
	global_load_lds_dwordx4 v[2:3], off
	v_lshrrev_b32_e32 v3, 1, v10
	v_and_b32_e32 v156, 24, v3
	v_and_b32_e32 v2, 15, v10
	v_lshlrev_b32_e32 v3, 1, v156
	v_lshl_or_b32 v1, s16, 6, v2
	v_lshl_or_b32 v2, v2, 6, v3
	v_lshlrev_b32_e32 v3, 2, v10
	v_and_b32_e32 v3, 32, v3
	v_bitop3_b32 v4, v2, s24, v3 bitop3:0xde
	v_bitop3_b32 v157, v2, s17, v3 bitop3:0xde
	v_lshlrev_b32_e32 v2, 14, v15
	v_and_b32_e32 v2, 0xffff8000, v2
	v_lshl_add_u32 v2, v14, 11, v2
	v_and_b32_e32 v3, 1, v15
	v_lshl_or_b32 v2, v3, 6, v2
	v_lshl_add_u32 v158, v16, 1, v2
	v_lshlrev_b32_e32 v2, 14, v11
	v_and_b32_e32 v2, 0xffff8000, v2
	s_waitcnt vmcnt(6)
	v_lshl_add_u32 v2, v12, 11, v2
	v_and_b32_e32 v3, 1, v11
	s_sext_i32_i8 s52, s14
	s_cselect_b64 s[14:15], -1, 0
	v_lshl_or_b32 v2, v3, 6, v2
	s_add_i32 s57, 0, 0x14000
	v_mov_b32_e32 v159, v155
	v_lshl_add_u32 v160, v13, 1, v2
	v_mov_b32_e32 v161, v155
	v_mov_b64_e32 v[162:163], 0x580
	v_mov_b64_e32 v[164:165], 0x57f
	v_add_u32_e32 v169, s3, v157
	v_add_u32_e32 v171, s57, v157
	v_add_u32_e32 v173, 0, v4
	s_movk_i32 s92, 0x1600
	v_mov_b32_e32 v177, 0x358637bd
	s_mov_b32 s93, 0
	s_barrier
	s_and_b64 vcc, exec, s[6:7]
	s_cbranch_vccz .Lp10_prio_done
	s_setprio 1
.Lp10_prio_done:
	s_branch .LBB0_1291
.LBB0_1289:
	s_mov_b64 s[20:21], 0

.LBB0_1294:
	ds_read_b128 v[70:73], v169
	ds_read_b128 v[78:81], v169 offset:1024
	ds_read_b128 v[82:85], v169 offset:2048
	ds_read_b128 v[94:97], v169 offset:3072
	ds_read_b128 v[178:181], v171
	ds_read_b128 v[182:185], v171 offset:1024
	ds_read_b128 v[186:189], v171 offset:2048
	ds_read_b128 v[190:193], v171 offset:3072
	s_add_u32 s22, s20, 0xfffc0080
	s_addc_u32 s23, s21, -1
	s_cmp_eq_u32 s39, 12
	s_cselect_b32 s25, s19, s23
	s_cselect_b32 s24, s53, s22
	s_cselect_b32 s23, s17, s38
	s_cselect_b32 s22, s94, s95
	v_lshl_add_u64 v[166:167], s[20:21], 0, v[158:159]
	s_add_i32 m0, s34, 0xc000
	ds_read_b128 v[194:197], v173
	ds_read_b128 v[198:201], v173 offset:1024
	ds_read_b128 v[202:205], v173 offset:2048
	ds_read_b128 v[206:209], v173 offset:3072
	ds_read_b128 v[210:213], v173 offset:4096
	ds_read_b128 v[214:217], v173 offset:5120
	ds_read_b128 v[218:221], v173 offset:6144
	ds_read_b128 v[222:225], v173 offset:7168
	global_load_lds_dwordx4 v[166:167], off
	v_lshl_add_u64 v[166:167], s[20:21], 0, v[160:161]
	s_add_i32 m0, s34, 0xe000
	s_nop 0
	global_load_lds_dwordx4 v[166:167], off
	s_waitcnt vmcnt(8)
	s_waitcnt lgkmcnt(0)
	s_barrier
	s_waitcnt lgkmcnt(0)
	v_mfma_f32_16x16x32_bf16 v[142:145], v[70:73], v[194:197], v[142:145]
	v_mfma_f32_16x16x32_bf16 v[138:141], v[82:85], v[194:197], v[138:141]
	v_mfma_f32_16x16x32_bf16 v[126:129], v[70:73], v[202:205], v[126:129]
	v_mfma_f32_16x16x32_bf16 v[122:125], v[82:85], v[202:205], v[122:125]
	v_mfma_f32_16x16x32_bf16 v[114:117], v[70:73], v[210:213], v[114:117]
	v_mfma_f32_16x16x32_bf16 v[110:113], v[82:85], v[210:213], v[110:113]
	v_mfma_f32_16x16x32_bf16 v[98:101], v[70:73], v[218:221], v[98:101]
	v_mfma_f32_16x16x32_bf16 v[90:93], v[82:85], v[218:221], v[90:93]
	v_mfma_f32_16x16x32_bf16 v[142:145], v[78:81], v[198:201], v[142:145]
	v_mfma_f32_16x16x32_bf16 v[138:141], v[94:97], v[198:201], v[138:141]
	v_mfma_f32_16x16x32_bf16 v[126:129], v[78:81], v[206:209], v[126:129]
	v_mfma_f32_16x16x32_bf16 v[122:125], v[94:97], v[206:209], v[122:125]
	v_mfma_f32_16x16x32_bf16 v[114:117], v[78:81], v[214:217], v[114:117]
	v_mfma_f32_16x16x32_bf16 v[110:113], v[94:97], v[214:217], v[110:113]
	v_mfma_f32_16x16x32_bf16 v[98:101], v[78:81], v[222:225], v[98:101]
	v_mfma_f32_16x16x32_bf16 v[90:93], v[94:97], v[222:225], v[90:93]
	v_mfma_f32_16x16x32_bf16 v[134:137], v[178:181], v[194:197], v[134:137]
	v_mfma_f32_16x16x32_bf16 v[130:133], v[186:189], v[194:197], v[130:133]
	v_mfma_f32_16x16x32_bf16 v[118:121], v[178:181], v[202:205], v[118:121]
	v_mfma_f32_16x16x32_bf16 v[106:109], v[186:189], v[202:205], v[106:109]
	v_mfma_f32_16x16x32_bf16 v[102:105], v[178:181], v[210:213], v[102:105]
	v_mfma_f32_16x16x32_bf16 v[86:89], v[186:189], v[210:213], v[86:89]
	v_mfma_f32_16x16x32_bf16 v[74:77], v[178:181], v[218:221], v[74:77]
	v_mfma_f32_16x16x32_bf16 v[66:69], v[186:189], v[218:221], v[66:69]
	v_mfma_f32_16x16x32_bf16 v[134:137], v[182:185], v[198:201], v[134:137]
	v_mfma_f32_16x16x32_bf16 v[130:133], v[190:193], v[198:201], v[130:133]
	v_mfma_f32_16x16x32_bf16 v[118:121], v[182:185], v[206:209], v[118:121]
	v_mfma_f32_16x16x32_bf16 v[106:109], v[190:193], v[206:209], v[106:109]
	v_mfma_f32_16x16x32_bf16 v[102:105], v[182:185], v[214:217], v[102:105]
	v_mfma_f32_16x16x32_bf16 v[86:89], v[190:193], v[214:217], v[86:89]
	v_mfma_f32_16x16x32_bf16 v[74:77], v[182:185], v[222:225], v[74:77]
	v_mfma_f32_16x16x32_bf16 v[66:69], v[190:193], v[222:225], v[66:69]
	s_barrier
	s_add_i32 s48, s3, s30
	v_lshl_add_u64 v[166:167], s[22:23], 0, v[150:151]
	s_mov_b32 m0, s48
	ds_read_b128 v[194:197], v173 offset:16384
	ds_read_b128 v[198:201], v173 offset:17408
	ds_read_b128 v[202:205], v173 offset:18432
	ds_read_b128 v[206:209], v173 offset:19456
	ds_read_b128 v[210:213], v173 offset:20480
	ds_read_b128 v[214:217], v173 offset:21504
	ds_read_b128 v[218:221], v173 offset:22528
	ds_read_b128 v[222:225], v173 offset:23552
	global_load_lds_dwordx4 v[166:167], off
	s_add_i32 m0, s48, 0x2000
	s_add_u32 s50, s22, 0x40000
	v_lshl_add_u64 v[174:175], s[22:23], 0, v[146:147]
	s_addc_u32 s51, s23, 0
	s_add_i32 s48, s57, s30
	global_load_lds_dwordx4 v[174:175], off
	v_lshl_add_u64 v[226:227], s[50:51], 0, v[150:151]
	s_mov_b32 m0, s48
	v_lshl_add_u64 v[228:229], s[24:25], 0, v[148:149]
	global_load_lds_dwordx4 v[226:227], off
	v_lshl_add_u64 v[226:227], s[50:51], 0, v[146:147]
	s_add_i32 m0, s48, 0x2000
	s_nop 0
	global_load_lds_dwordx4 v[226:227], off
	v_lshl_add_u64 v[226:227], s[24:25], 0, v[152:153]
	s_mov_b32 m0, s34
	s_nop 0
	global_load_lds_dwordx4 v[226:227], off
	s_mov_b32 m0, s35
	s_nop 0
	global_load_lds_dwordx4 v[228:229], off
	s_waitcnt vmcnt(8)
	s_waitcnt lgkmcnt(0)
	s_barrier
	s_waitcnt lgkmcnt(0)
	v_mfma_f32_16x16x32_bf16 v[62:65], v[70:73], v[194:197], v[62:65]
	v_mfma_f32_16x16x32_bf16 v[58:61], v[82:85], v[194:197], v[58:61]
	v_mfma_f32_16x16x32_bf16 v[50:53], v[70:73], v[202:205], v[50:53]
	v_mfma_f32_16x16x32_bf16 v[46:49], v[82:85], v[202:205], v[46:49]
	v_mfma_f32_16x16x32_bf16 v[34:37], v[70:73], v[210:213], v[34:37]
	v_mfma_f32_16x16x32_bf16 v[30:33], v[82:85], v[210:213], v[30:33]
	v_mfma_f32_16x16x32_bf16 v[18:21], v[70:73], v[218:221], v[18:21]
	v_mfma_f32_16x16x32_bf16 v[14:17], v[82:85], v[218:221], v[14:17]
	v_mfma_f32_16x16x32_bf16 v[62:65], v[78:81], v[198:201], v[62:65]
	v_mfma_f32_16x16x32_bf16 v[58:61], v[94:97], v[198:201], v[58:61]
	v_mfma_f32_16x16x32_bf16 v[50:53], v[78:81], v[206:209], v[50:53]
	v_mfma_f32_16x16x32_bf16 v[46:49], v[94:97], v[206:209], v[46:49]
	v_mfma_f32_16x16x32_bf16 v[34:37], v[78:81], v[214:217], v[34:37]
	v_mfma_f32_16x16x32_bf16 v[30:33], v[94:97], v[214:217], v[30:33]
	v_mfma_f32_16x16x32_bf16 v[18:21], v[78:81], v[222:225], v[18:21]
	v_mfma_f32_16x16x32_bf16 v[14:17], v[94:97], v[222:225], v[14:17]
	v_mfma_f32_16x16x32_bf16 v[54:57], v[178:181], v[194:197], v[54:57]
	v_mfma_f32_16x16x32_bf16 v[42:45], v[186:189], v[194:197], v[42:45]
	v_mfma_f32_16x16x32_bf16 v[38:41], v[178:181], v[202:205], v[38:41]
	v_mfma_f32_16x16x32_bf16 v[26:29], v[186:189], v[202:205], v[26:29]
	v_mfma_f32_16x16x32_bf16 v[22:25], v[178:181], v[210:213], v[22:25]
	v_mfma_f32_16x16x32_bf16 v[10:13], v[186:189], v[210:213], v[10:13]
	v_mfma_f32_16x16x32_bf16 v[6:9], v[178:181], v[218:221], v[6:9]
	v_mfma_f32_16x16x32_bf16 v[2:5], v[186:189], v[218:221], v[2:5]
	v_mfma_f32_16x16x32_bf16 v[54:57], v[182:185], v[198:201], v[54:57]
	v_mfma_f32_16x16x32_bf16 v[42:45], v[190:193], v[198:201], v[42:45]
	v_mfma_f32_16x16x32_bf16 v[38:41], v[182:185], v[206:209], v[38:41]
	v_mfma_f32_16x16x32_bf16 v[26:29], v[190:193], v[206:209], v[26:29]
	v_mfma_f32_16x16x32_bf16 v[22:25], v[182:185], v[214:217], v[22:25]
	v_mfma_f32_16x16x32_bf16 v[10:13], v[190:193], v[214:217], v[10:13]
	v_mfma_f32_16x16x32_bf16 v[6:9], v[182:185], v[222:225], v[6:9]
	v_mfma_f32_16x16x32_bf16 v[2:5], v[190:193], v[222:225], v[2:5]
	s_barrier
	s_add_i32 s48, 0, 0x18000
	s_add_i32 s49, 0, 0x1c000
	v_add_u32_e32 v94, s48, v157
	v_add_u32_e32 v154, s49, v157
	ds_read_b128 v[70:73], v94
	ds_read_b128 v[78:81], v94 offset:1024
	ds_read_b128 v[82:85], v94 offset:2048
	ds_read_b128 v[94:97], v94 offset:3072
	ds_read_b128 v[178:181], v154
	ds_read_b128 v[182:185], v154 offset:1024
	ds_read_b128 v[186:189], v154 offset:2048
	ds_read_b128 v[190:193], v154 offset:3072
	s_add_u32 s24, s24, 0x40000
	s_addc_u32 s25, s25, 0
	s_mov_b32 m0, s44
	v_lshl_add_u64 v[230:231], s[24:25], 0, v[152:153]
	ds_read_b128 v[194:197], v173 offset:32768
	ds_read_b128 v[198:201], v173 offset:33792
	ds_read_b128 v[202:205], v173 offset:34816
	ds_read_b128 v[206:209], v173 offset:35840
	ds_read_b128 v[210:213], v173 offset:36864
	ds_read_b128 v[214:217], v173 offset:37888
	ds_read_b128 v[218:221], v173 offset:38912
	ds_read_b128 v[222:225], v173 offset:39936
	global_load_lds_dwordx4 v[230:231], off
	v_lshl_add_u64 v[230:231], s[24:25], 0, v[148:149]
	s_mov_b32 m0, s45
	s_nop 0
	global_load_lds_dwordx4 v[230:231], off
	s_waitcnt vmcnt(8)
	s_waitcnt lgkmcnt(0)
	s_barrier
	s_waitcnt lgkmcnt(0)
	v_mfma_f32_16x16x32_bf16 v[142:145], v[70:73], v[194:197], v[142:145]
	v_mfma_f32_16x16x32_bf16 v[138:141], v[82:85], v[194:197], v[138:141]
	v_mfma_f32_16x16x32_bf16 v[126:129], v[70:73], v[202:205], v[126:129]
	v_mfma_f32_16x16x32_bf16 v[122:125], v[82:85], v[202:205], v[122:125]
	v_mfma_f32_16x16x32_bf16 v[114:117], v[70:73], v[210:213], v[114:117]
	v_mfma_f32_16x16x32_bf16 v[110:113], v[82:85], v[210:213], v[110:113]
	v_mfma_f32_16x16x32_bf16 v[98:101], v[70:73], v[218:221], v[98:101]
	v_mfma_f32_16x16x32_bf16 v[90:93], v[82:85], v[218:221], v[90:93]
	v_mfma_f32_16x16x32_bf16 v[142:145], v[78:81], v[198:201], v[142:145]
	v_mfma_f32_16x16x32_bf16 v[138:141], v[94:97], v[198:201], v[138:141]
	v_mfma_f32_16x16x32_bf16 v[126:129], v[78:81], v[206:209], v[126:129]
	v_mfma_f32_16x16x32_bf16 v[122:125], v[94:97], v[206:209], v[122:125]
	v_mfma_f32_16x16x32_bf16 v[114:117], v[78:81], v[214:217], v[114:117]
	v_mfma_f32_16x16x32_bf16 v[110:113], v[94:97], v[214:217], v[110:113]
	v_mfma_f32_16x16x32_bf16 v[98:101], v[78:81], v[222:225], v[98:101]
	v_mfma_f32_16x16x32_bf16 v[90:93], v[94:97], v[222:225], v[90:93]
	v_mfma_f32_16x16x32_bf16 v[134:137], v[178:181], v[194:197], v[134:137]
	v_mfma_f32_16x16x32_bf16 v[130:133], v[186:189], v[194:197], v[130:133]
	v_mfma_f32_16x16x32_bf16 v[118:121], v[178:181], v[202:205], v[118:121]
	v_mfma_f32_16x16x32_bf16 v[106:109], v[186:189], v[202:205], v[106:109]
	v_mfma_f32_16x16x32_bf16 v[102:105], v[178:181], v[210:213], v[102:105]
	v_mfma_f32_16x16x32_bf16 v[86:89], v[186:189], v[210:213], v[86:89]
	v_mfma_f32_16x16x32_bf16 v[74:77], v[178:181], v[218:221], v[74:77]
	v_mfma_f32_16x16x32_bf16 v[66:69], v[186:189], v[218:221], v[66:69]
	v_mfma_f32_16x16x32_bf16 v[134:137], v[182:185], v[198:201], v[134:137]
	v_mfma_f32_16x16x32_bf16 v[130:133], v[190:193], v[198:201], v[130:133]
	v_mfma_f32_16x16x32_bf16 v[118:121], v[182:185], v[206:209], v[118:121]
	v_mfma_f32_16x16x32_bf16 v[106:109], v[190:193], v[206:209], v[106:109]
	v_mfma_f32_16x16x32_bf16 v[102:105], v[182:185], v[214:217], v[102:105]
	v_mfma_f32_16x16x32_bf16 v[86:89], v[190:193], v[214:217], v[86:89]
	v_mfma_f32_16x16x32_bf16 v[74:77], v[182:185], v[222:225], v[74:77]
	v_mfma_f32_16x16x32_bf16 v[66:69], v[190:193], v[222:225], v[66:69]
	s_barrier
	s_add_i32 s24, s48, s30
	v_lshl_add_u64 v[166:167], v[166:167], 0, s[12:13]
	s_mov_b32 m0, s24
	ds_read_b128 v[194:197], v173 offset:49152
	ds_read_b128 v[198:201], v173 offset:50176
	ds_read_b128 v[202:205], v173 offset:51200
	ds_read_b128 v[206:209], v173 offset:52224
	ds_read_b128 v[210:213], v173 offset:53248
	ds_read_b128 v[214:217], v173 offset:54272
	ds_read_b128 v[218:221], v173 offset:55296
	ds_read_b128 v[222:225], v173 offset:56320
	global_load_lds_dwordx4 v[166:167], off
	s_add_i32 m0, s24, 0x2000
	s_add_u32 s22, s22, 0x40080
	v_lshl_add_u64 v[166:167], v[174:175], 0, s[12:13]
	s_addc_u32 s23, s23, 0
	s_add_i32 s24, s49, s30
	global_load_lds_dwordx4 v[166:167], off
	v_lshl_add_u64 v[166:167], s[22:23], 0, v[150:151]
	s_mov_b32 m0, s24
	s_nop 0
	global_load_lds_dwordx4 v[166:167], off
	v_lshl_add_u64 v[166:167], s[22:23], 0, v[146:147]
	s_add_i32 m0, s24, 0x2000
	s_nop 0
	global_load_lds_dwordx4 v[166:167], off
	v_lshl_add_u64 v[166:167], v[226:227], 0, s[12:13]
	s_mov_b32 m0, s55
	s_nop 0
	global_load_lds_dwordx4 v[166:167], off
	v_lshl_add_u64 v[166:167], v[228:229], 0, s[12:13]
	s_mov_b32 m0, s56
	s_nop 0
	global_load_lds_dwordx4 v[166:167], off
	s_waitcnt vmcnt(8)
	s_waitcnt lgkmcnt(0)
	s_barrier
	s_waitcnt lgkmcnt(0)
	v_mfma_f32_16x16x32_bf16 v[62:65], v[70:73], v[194:197], v[62:65]
	v_mfma_f32_16x16x32_bf16 v[58:61], v[82:85], v[194:197], v[58:61]
	v_mfma_f32_16x16x32_bf16 v[50:53], v[70:73], v[202:205], v[50:53]
	v_mfma_f32_16x16x32_bf16 v[46:49], v[82:85], v[202:205], v[46:49]
	v_mfma_f32_16x16x32_bf16 v[34:37], v[70:73], v[210:213], v[34:37]
	v_mfma_f32_16x16x32_bf16 v[30:33], v[82:85], v[210:213], v[30:33]
	v_mfma_f32_16x16x32_bf16 v[18:21], v[70:73], v[218:221], v[18:21]
	v_mfma_f32_16x16x32_bf16 v[14:17], v[82:85], v[218:221], v[14:17]
	v_mfma_f32_16x16x32_bf16 v[62:65], v[78:81], v[198:201], v[62:65]
	v_mfma_f32_16x16x32_bf16 v[58:61], v[94:97], v[198:201], v[58:61]
	v_mfma_f32_16x16x32_bf16 v[50:53], v[78:81], v[206:209], v[50:53]
	v_mfma_f32_16x16x32_bf16 v[46:49], v[94:97], v[206:209], v[46:49]
	v_mfma_f32_16x16x32_bf16 v[34:37], v[78:81], v[214:217], v[34:37]
	v_mfma_f32_16x16x32_bf16 v[30:33], v[94:97], v[214:217], v[30:33]
	v_mfma_f32_16x16x32_bf16 v[18:21], v[78:81], v[222:225], v[18:21]
	v_mfma_f32_16x16x32_bf16 v[14:17], v[94:97], v[222:225], v[14:17]
	v_mfma_f32_16x16x32_bf16 v[54:57], v[178:181], v[194:197], v[54:57]
	v_mfma_f32_16x16x32_bf16 v[42:45], v[186:189], v[194:197], v[42:45]
	v_mfma_f32_16x16x32_bf16 v[38:41], v[178:181], v[202:205], v[38:41]
	v_mfma_f32_16x16x32_bf16 v[26:29], v[186:189], v[202:205], v[26:29]
	v_mfma_f32_16x16x32_bf16 v[22:25], v[178:181], v[210:213], v[22:25]
	v_mfma_f32_16x16x32_bf16 v[10:13], v[186:189], v[210:213], v[10:13]
	v_mfma_f32_16x16x32_bf16 v[6:9], v[178:181], v[218:221], v[6:9]
	v_mfma_f32_16x16x32_bf16 v[2:5], v[186:189], v[218:221], v[2:5]
	v_mfma_f32_16x16x32_bf16 v[54:57], v[182:185], v[198:201], v[54:57]
	v_mfma_f32_16x16x32_bf16 v[42:45], v[190:193], v[198:201], v[42:45]
	v_mfma_f32_16x16x32_bf16 v[38:41], v[182:185], v[206:209], v[38:41]
	v_mfma_f32_16x16x32_bf16 v[26:29], v[190:193], v[206:209], v[26:29]
	v_mfma_f32_16x16x32_bf16 v[22:25], v[182:185], v[214:217], v[22:25]
	v_mfma_f32_16x16x32_bf16 v[10:13], v[190:193], v[214:217], v[10:13]
	v_mfma_f32_16x16x32_bf16 v[6:9], v[182:185], v[222:225], v[6:9]
	v_mfma_f32_16x16x32_bf16 v[2:5], v[190:193], v[222:225], v[2:5]
	s_barrier
	s_add_i32 s39, s39, 2
	s_add_u32 s20, s20, 0x100
	s_addc_u32 s21, s21, 0
	s_add_u32 s95, s95, 0x100
	s_addc_u32 s38, s38, 0
	s_cmp_gt_u32 s39, 13
	s_cbranch_scc0 .LBB0_1294
	s_and_b64 vcc, exec, s[14:15]
	s_cbranch_vccz .LBB0_1297
	s_barrier

.LBB0_1300:
	s_setprio 0
	s_waitcnt vmcnt(0)
	v_readlane_b32 s90, v255, 10
	v_readlane_b32 s56, v255, 20
	v_readlane_b32 s91, v255, 11
	v_readlane_b32 s57, v255, 21
	s_mov_b64 s[50:51], s[96:97]
	s_barrier
